# SB static-path prologue: issue q, kmax and all 16 K/V loads back to back before the q-norm (1 exposed latency instead of 3); dynamic path q wait moved below first 10 K/V loads
# speedup vs baseline: 1.0096x; 1.0034x over previous
; #define LAS __attribute__((address_space(3)))
; __device__ __forceinline__ float bflo(unsigned u) { return __uint_as_float(u << 16); }
; __device__ __forceinline__ float bfhi(unsigned u) { return __uint_as_float(u & 0xffff0000u); }
; __device__ __forceinline__ float sx(float v, int m, int lane) { return __builtin_bit_cast(float, __builtin_amdgcn_ds_bpermute((lane ^ m) << 2, __builtin_bit_cast(int, v))); }
; __device__ __forceinline__ void sb_item(const bf16_t* hbuf, const float* kmax2, bf16_t* mixed, LAS bf16_t* vT, int item, int lane) {
;     const int bh = item >> 10, qt = item & 1023, b = bh / 6, h = bh % 6, tq0 = qt * 16; const size_t row0 = (size_t)b * SEQ + tq0;
;     const int r = lane & 15, q = lane >> 4;
;     bf16x8 qf[2]; float bound, carry = 0.f;
;     const float km2 = kmax2[bh];
;     { float s = 0.f;
; #pragma unroll
;       for (int ks = 0; ks < 2; ++ks) { const u32x4 v = *(const u32x4*)(hbuf + (row0 + r) * INWP + C_SBQ + h * 64 + 32 * ks + 8 * q); qf[ks] = as_bf16x8(v);
;           s += bflo(v.x) * bflo(v.x) + bfhi(v.x) * bfhi(v.x) + bflo(v.y) * bflo(v.y) + bfhi(v.y) * bfhi(v.y) + bflo(v.z) * bflo(v.z) + bfhi(v.z) * bfhi(v.z) + bflo(v.w) * bflo(v.w) + bfhi(v.w) * bfhi(v.w); }
;       s += sx(s, 16, lane); s += sx(s, 32, lane);
;       bound = sqrtf(s * km2) * 0.125f * 1.01f + 0.05f; }
;     const int qpos = tq0 + r;
;     f32x4 O[4];
; #pragma unroll
;     for (int et = 0; et < 4; ++et) O[et] = (f32x4){0.f, 0.f, 0.f, 0.f};
;     const int cr = lane >> 3, dc = lane & 7;
;     const bf16_t* seqp = hbuf + (size_t)b * SEQ * INWP + h * 64;
;     u32x4 vreg[8], kreg[8];
;     { const int k0 = tq0 + 16 - 64;
; #pragma unroll
;       for (int i = 0; i < 8; ++i) vreg[i] = *(const u32x4*)(seqp + (size_t)max(k0 + cr + 8 * i, 0) * INWP + C_SBV + 8 * dc);
; #pragma unroll
;       for (int i = 0; i < 8; ++i) kreg[i] = *(const u32x4*)(seqp + (size_t)max(k0 + 16 * (i >> 1) + r, 0) * INWP + C_SBK + 32 * (i & 1) + 8 * q); }
.LBB0_234:
	s_and_b32 s98, s12, 3
	s_lshl_b32 s98, s98, 3
	s_bfe_u32 s99, s12, 0x30002
	s_add_i32 s98, s98, s99
	s_and_b32 s99, s12, 0xffffffe0
	s_or_b32 s98, s98, s99
	s_ashr_i32 s0, s98, 10
	s_mul_hi_i32 s1, s0, 0x2aaaaaab
	s_lshr_b32 s17, s1, 31
	s_add_i32 s20, s1, s17
	s_mul_i32 s1, s20, 6
	s_sub_i32 s17, s0, s1
	s_lshl_b32 s1, s98, 4
	s_ashr_i32 s21, s20, 31
	s_and_b32 s26, s1, 0x3ff0
	s_lshl_b64 s[22:23], s[20:21], 14
	s_ashr_i32 s1, s0, 31
	s_or_b32 s21, s22, s26
	s_lshl_b64 s[0:1], s[0:1], 2
	s_add_u32 s0, s75, s0
	s_addc_u32 s1, s74, s1
	v_or_b32_e32 v34, s21, v122
	v_mov_b64_e32 v[8:9], s[42:43]
	s_lshl_b32 s72, s17, 6
	global_load_dword v214, v33, s[0:1] offset:1024
	v_mad_u64_u32 v[8:9], s[0:1], v34, s5, v[8:9]
	s_ashr_i32 s73, s72, 31
	v_mov_b32_e32 v35, s23
	v_mad_i32_i24 v9, s23, v207, v9
	s_lshl_b64 s[22:23], s[72:73], 1
	v_lshl_add_u64 v[8:9], v[8:9], 0, s[22:23]
	v_lshlrev_b32_e32 v32, 1, v124
	v_lshl_add_u64 v[12:13], v[8:9], 0, v[32:33]
	global_load_dwordx4 v[8:11], v[12:13], off offset:512
	v_lshlrev_b32_e32 v88, 1, v126
	v_mov_b32_e32 v89, v33
	v_mov_b32_e32 v153, 0
	v_or_b32_e32 v155, s26, v122
	v_mov_b32_e32 v100, 0
	v_mov_b32_e32 v101, v153
	v_mov_b32_e32 v102, v153
	v_mov_b32_e32 v103, v153
	v_mov_b32_e32 v96, 0
	v_mov_b32_e32 v97, v153
	v_mov_b32_e32 v98, v153
	v_mov_b32_e32 v99, v153
	v_mov_b32_e32 v92, 0
	v_mov_b32_e32 v93, v153
	v_mov_b32_e32 v94, v153
	v_mov_b32_e32 v95, v153
	v_mov_b32_e32 v90, v153
	v_mov_b32_e32 v91, v153
	global_load_dwordx4 v[12:15], v[12:13], off offset:576
	s_waitcnt vmcnt(7)
	s_mul_i32 s1, s20, 0x6000000
	s_mul_hi_i32 s0, s20, 0x6000000
	s_add_u32 s1, s42, s1
	s_addc_u32 s17, s43, s0
	s_add_u32 s0, s1, s22
	s_addc_u32 s1, s17, s23
	s_sub_i32 s17, s26, 48
	v_or_b32_e32 v48, s17, v122
	v_or_b32_e32 v86, s17, v134
	v_max_i32_e32 v16, 0xffffffd0, v48
	v_max_i32_e32 v24, 0xffffffe0, v48
	v_max_i32_e32 v40, -16, v48
	v_max_i32_e32 v64, 0xffffffd8, v86
	v_max_i32_e32 v68, 0xffffffe0, v86
	v_add_u32_e32 v16, 48, v16
	v_mov_b64_e32 v[84:85], s[0:1]
	v_add_u32_e32 v24, 32, v24
	v_add_u32_e32 v40, 16, v40
	v_max_i32_e32 v48, 0, v48
	v_add_u32_e32 v64, 40, v64
	v_add_u32_e32 v68, 32, v68
	v_mad_u64_u32 v[16:17], s[20:21], v16, s5, v[84:85]
	v_mad_u64_u32 v[24:25], s[20:21], v24, s5, v[84:85]
	v_mad_u64_u32 v[40:41], s[20:21], v40, s5, v[84:85]
	v_mad_u64_u32 v[48:49], s[20:21], v48, s5, v[84:85]
	v_mad_u64_u32 v[64:65], s[20:21], v64, s5, v[84:85]
	v_mad_u64_u32 v[68:69], s[20:21], v68, s5, v[84:85]
	v_lshl_add_u64 v[20:21], v[16:17], 0, v[32:33]
	v_lshl_add_u64 v[28:29], v[24:25], 0, v[32:33]
	v_lshl_add_u64 v[44:45], v[40:41], 0, v[32:33]
	v_lshl_add_u64 v[52:53], v[48:49], 0, v[32:33]
	v_lshl_add_u64 v[64:65], v[64:65], 0, v[88:89]
	v_lshl_add_u64 v[68:69], v[68:69], 0, v[88:89]
	global_load_dwordx4 v[16:19], v[20:21], off offset:1344
	s_nop 0
	global_load_dwordx4 v[20:23], v[20:21], off offset:1280
	s_nop 0
	global_load_dwordx4 v[24:27], v[28:29], off offset:1344
	s_nop 0
	global_load_dwordx4 v[28:31], v[28:29], off offset:1280
	s_nop 0
	global_load_dwordx4 v[40:43], v[44:45], off offset:1344
	s_nop 0
	global_load_dwordx4 v[44:47], v[44:45], off offset:1280
	s_nop 0
	global_load_dwordx4 v[48:51], v[52:53], off offset:1344
	s_nop 0
	global_load_dwordx4 v[52:55], v[52:53], off offset:1280
	v_max_i32_e32 v76, -16, v86
	global_load_dwordx4 v[64:67], v[64:65], off offset:2048
	v_add_u32_e32 v76, 16, v76
	global_load_dwordx4 v[72:75], v[68:69], off offset:2048
	v_max_i32_e32 v68, 0xffffffe8, v86
	v_add_u32_e32 v68, 24, v68
	v_mad_u64_u32 v[68:69], s[20:21], v68, s5, v[84:85]
	v_mad_u64_u32 v[76:77], s[20:21], v76, s5, v[84:85]
	v_lshl_add_u64 v[68:69], v[68:69], 0, v[88:89]
	v_lshl_add_u64 v[76:77], v[76:77], 0, v[88:89]
	v_max_i32_e32 v56, 0xffffffc8, v86
	v_max_i32_e32 v60, 0xffffffd0, v86
	global_load_dwordx4 v[68:71], v[68:69], off offset:2048
	v_add_u32_e32 v56, 56, v56
	global_load_dwordx4 v[80:83], v[76:77], off offset:2048
	v_or_b32_e32 v76, 8, v86
	v_add_u32_e32 v60, 48, v60
	v_max_i32_e32 v76, 0, v76
	v_max_i32_e32 v86, 0, v86
	v_mad_u64_u32 v[56:57], s[20:21], v56, s5, v[84:85]
	v_mad_u64_u32 v[60:61], s[20:21], v60, s5, v[84:85]
	v_mad_u64_u32 v[76:77], s[20:21], v76, s5, v[84:85]
	v_mad_u64_u32 v[84:85], s[20:21], v86, s5, v[84:85]
	v_lshl_add_u64 v[56:57], v[56:57], 0, v[88:89]
	v_lshl_add_u64 v[60:61], v[60:61], 0, v[88:89]
	v_lshl_add_u64 v[76:77], v[76:77], 0, v[88:89]
	v_lshl_add_u64 v[84:85], v[84:85], 0, v[88:89]
	global_load_dwordx4 v[56:59], v[56:57], off offset:2048
	v_lshl_add_u64 v[128:129], s[0:1], 0, v[88:89]
	global_load_dwordx4 v[60:63], v[60:61], off offset:2048
	v_lshl_add_u64 v[130:131], s[0:1], 0, v[32:33]
	global_load_dwordx4 v[76:79], v[76:77], off offset:2048
	v_mov_b32_e32 v88, 0
	global_load_dwordx4 v[84:87], v[84:85], off offset:2048
	v_mov_b32_e32 v89, v153
	s_mov_b32 s98, 0xf800000
	s_waitcnt vmcnt(16)
	v_and_b32_e32 v216, 0xffff0000, v8
	v_lshlrev_b32_e32 v215, 16, v8
	v_mul_f32_e32 v217, v216, v216
	v_fmac_f32_e32 v217, v215, v215
	v_lshlrev_b32_e32 v215, 16, v9
	v_fmac_f32_e32 v217, v215, v215
	v_and_b32_e32 v215, 0xffff0000, v9
	v_fmac_f32_e32 v217, v215, v215
	v_lshlrev_b32_e32 v215, 16, v10
	v_fmac_f32_e32 v217, v215, v215
	v_and_b32_e32 v215, 0xffff0000, v10
	v_fmac_f32_e32 v217, v215, v215
	v_lshlrev_b32_e32 v215, 16, v11
	v_fmac_f32_e32 v217, v215, v215
	v_and_b32_e32 v215, 0xffff0000, v11
	v_fmac_f32_e32 v217, v215, v215
	v_and_b32_e32 v219, 0xffff0000, v12
	v_lshlrev_b32_e32 v218, 16, v12
	v_mul_f32_e32 v219, v219, v219
	v_fmac_f32_e32 v219, v218, v218
	v_lshlrev_b32_e32 v218, 16, v13
	v_fmac_f32_e32 v219, v218, v218
	v_and_b32_e32 v218, 0xffff0000, v13
	v_fmac_f32_e32 v219, v218, v218
	v_lshlrev_b32_e32 v218, 16, v14
	v_fmac_f32_e32 v219, v218, v218
	v_and_b32_e32 v218, 0xffff0000, v14
	v_fmac_f32_e32 v219, v218, v218
	v_lshlrev_b32_e32 v218, 16, v15
	v_fmac_f32_e32 v219, v218, v218
	v_and_b32_e32 v218, 0xffff0000, v15
	v_fmac_f32_e32 v219, v218, v218
	v_add_f32_e32 v217, v217, v219
	ds_bpermute_b32 v218, v132, v217
	s_waitcnt lgkmcnt(0)
	v_add_f32_e32 v217, v217, v218
	ds_bpermute_b32 v218, v133, v217
	s_waitcnt lgkmcnt(0)
	v_add_f32_e32 v217, v217, v218
	v_mul_f32_e32 v214, v214, v217
	v_cmp_gt_f32_e32 vcc, s98, v214
	v_mul_f32_e32 v217, 0x4f800000, v214
	s_nop 0
	v_cndmask_b32_e32 v214, v214, v217, vcc
	v_sqrt_f32_e32 v217, v214
	s_nop 0
	v_add_u32_e32 v218, -1, v217
	v_fma_f32 v219, -v218, v217, v214
	v_cmp_ge_f32_e64 s[100:101], 0, v219
	v_add_u32_e32 v219, 1, v217
	s_nop 0
	v_cndmask_b32_e64 v218, v217, v218, s[100:101]
	v_fma_f32 v217, -v219, v217, v214
	v_cmp_lt_f32_e64 s[100:101], 0, v217
	s_nop 1
	v_cndmask_b32_e64 v217, v218, v219, s[100:101]
	v_mul_f32_e32 v218, 0x37800000, v217
	v_cndmask_b32_e32 v217, v217, v218, vcc
	v_cmp_class_f32_e32 vcc, v214, v209
	v_cndmask_b32_e32 v214, v217, v214, vcc
	v_mul_f32_e32 v214, 0x3e000000, v214
	v_fmamk_f32 v154, v214, 0x3f8147ae, v170
	s_branch .LBB0_236
